# M1 work queue: the 32 sample-stream attention items (slowest) are issued first instead of last
# speedup vs baseline: 1.0102x; 1.0102x over previous
; __device__ __forceinline__ int lane_id() { int t; asm volatile("v_mbcnt_lo_u32_b32 %0, -1, 0\n\tv_mbcnt_hi_u32_b32 %0, -1, %0" : "=&v"(t)); return t; }
; __device__ __forceinline__ void attn_item(const Params& P, int l, LAS unsigned char* lds, int item, const int wv) {
;     ...
;     if (!smp) { const int c = item >> 2; hp = item & 3; q0 = 64 * c; nq = 64; const int c0 = c > 8 ? c - 8 : 0; kbase = 64 * c0; nkt = c - c0 + 1; qpos0 = q0; kpos0 = kbase; }
;     else { const int it = item - 512; s = it >> 2; hp = it & 3; q0 = TP + 16 * s; nq = 16; kbase = 0; nkt = 9; qpos0 = 1024; kpos0 = 512; }
; __global__ void __launch_bounds__(512, 2) fwd_megakernel(Params P) {
;     ...
;           while (it < N_ATT_ITEMS + N_LA_ITEMS) {
;               unsigned nx = 0; if (wv == 0 && lane_id() == 0) nx = __hip_atomic_fetch_add(ctr, 1u, __ATOMIC_RELAXED, __HIP_MEMORY_SCOPE_AGENT);
;               if (it < N_ATT_ITEMS) attn_item(P, l, lds, it, wv); else la_state_item(P, l, lds, it - N_ATT_ITEMS, wv);
.LBB0_300:
	s_cmpk_gt_i32 s20, 0x21f
	s_cbranch_scc1 .Lattn_noremap
	s_add_i32 s0, s20, 0x200
	s_add_i32 s1, s20, 0xffffffe0
	s_cmp_lt_u32 s20, 32
	s_cselect_b32 s20, s0, s1
